# P3b indexer score loop: two key tiles per step back to back, LDS reads up front, second accumulator set
# speedup vs baseline: 1.0308x; 1.0003x over previous
; #define LAS __attribute__((address_space(3)))
; __device__ __forceinline__ float psum32(float x) { const u32x2s r = __builtin_amdgcn_permlane32_swap(__float_as_uint(x), __float_as_uint(x), false, false); return __uint_as_float(r[0]) + __uint_as_float(r[1]); }
; __device__ __forceinline__ float relu_i(float x) { return __int_as_float(max(__float_as_int(x), 0)); }
; __device__ __forceinline__ void p3_indexer(const Params& p, unsigned char* lds, int bid, int nb, int rep_sc, int rep_sel) {
;     ...
;       for (int gr = 0; gr < ngr; ++gr) {
;         if (gr + 1 < ngr) *(LAS u32x4*)(stgb + ((gr + 1) & 1) * 8192 + tid * 16) = sv;
;         if (gr + 2 < ngr) sv = *(const u32x4*)(kb + (size_t)(gr + 2) * 8192);
;         const LAS unsigned char* bb = stgb + (gr & 1) * 8192 + lane * 16;
; #pragma unroll
;         for (int q = 0; q < 2; ++q) {
;           f32x16 acc;
; #pragma unroll
;           for (int i = 0; i < 16; ++i) acc[i] = 0.f;
; #pragma unroll
;           for (int ks = 0; ks < 4; ++ks) { const bf16x8 bfr = *(const LAS bf16x8*)(bb + q * 4096 + ks * 1024); acc = __builtin_amdgcn_mfma_f32_32x32x16_bf16(aq[ks], bfr, acc, 0, 0, 0); }
;           float s0 = 0.f, s1 = 0.f;
; #pragma unroll
;           for (int i = 0; i < 8; ++i) { s0 += wv[i] * relu_i(acc[i]); s1 += wv[8 + i] * relu_i(acc[8 + i]); }
;           s0 = psum32(s0); s1 = psum32(s1);
;           sc[(2 * wid + h) * 2048 + 32 * (2 * gr + q) + l31] = h ? s1 : s0;
;         }
;         __syncthreads();
;       }
.LBB0_594:
	s_and_b32 s18, s14, 0x2000
	v_add_u32_e32 v82, s18, v120
	ds_read_b128 v[222:225], v82
	ds_read_b128 v[226:229], v82 offset:1024
	ds_read_b128 v[230:233], v82 offset:2048
	ds_read_b128 v[234:237], v82 offset:3072
	ds_read_b128 v[238:241], v82 offset:4096
	ds_read_b128 v[242:245], v82 offset:5120
	ds_read_b128 v[246:249], v82 offset:6144
	ds_read_b128 v[250:253], v82 offset:7168
	s_add_u32 s14, s14, 0x2000
	s_addc_u32 s15, s15, 0
	s_cmp_eq_u32 s16, s17
	s_mov_b32 s18, s17
	s_waitcnt lgkmcnt(7)
	v_mfma_f32_32x32x16_bf16 v[0:15], v[20:23], v[222:225], 0
	s_waitcnt lgkmcnt(6)
	v_mfma_f32_32x32x16_bf16 v[0:15], v[24:27], v[226:229], v[0:15]
	s_waitcnt vmcnt(2) lgkmcnt(5)
	v_mfma_f32_32x32x16_bf16 v[0:15], v[28:31], v[230:233], v[0:15]
	s_waitcnt vmcnt(1) lgkmcnt(4)
	v_mfma_f32_32x32x16_bf16 v[0:15], v[32:35], v[234:237], v[0:15]
	s_waitcnt lgkmcnt(3)
	v_mfma_f32_32x32x16_bf16 v[206:221], v[20:23], v[238:241], 0
	s_waitcnt lgkmcnt(2)
	v_mfma_f32_32x32x16_bf16 v[206:221], v[24:27], v[242:245], v[206:221]
	s_waitcnt vmcnt(2) lgkmcnt(1)
	v_mfma_f32_32x32x16_bf16 v[206:221], v[28:31], v[246:249], v[206:221]
	s_waitcnt vmcnt(1) lgkmcnt(0)
	v_mfma_f32_32x32x16_bf16 v[206:221], v[32:35], v[250:253], v[206:221]
	s_nop 3
	v_max_i32_e32 v0, 0, v0
	v_max_i32_e32 v8, 0, v8
	v_max_i32_e32 v1, 0, v1
	v_max_i32_e32 v9, 0, v9
	v_fma_f32 v0, v40, v0, 0
	v_fma_f32 v8, v64, v8, 0
	v_max_i32_e32 v2, 0, v2
	v_max_i32_e32 v10, 0, v10
	v_fmac_f32_e32 v0, v52, v1
	v_fmac_f32_e32 v8, v68, v9
	v_max_i32_e32 v3, 0, v3
	v_max_i32_e32 v11, 0, v11
	v_fmac_f32_e32 v0, v56, v2
	v_fmac_f32_e32 v8, v72, v10
	v_max_i32_e32 v4, 0, v4
	v_max_i32_e32 v12, 0, v12
	v_fmac_f32_e32 v0, v60, v3
	v_fmac_f32_e32 v8, v76, v11
	v_max_i32_e32 v5, 0, v5
	v_max_i32_e32 v13, 0, v13
	v_fmac_f32_e32 v0, v50, v4
	v_fmac_f32_e32 v8, v66, v12
	v_max_i32_e32 v6, 0, v6
	v_max_i32_e32 v14, 0, v14
	v_fmac_f32_e32 v0, v54, v5
	v_fmac_f32_e32 v8, v70, v13
	v_max_i32_e32 v7, 0, v7
	v_max_i32_e32 v15, 0, v15
	v_fmac_f32_e32 v0, v58, v6
	v_fmac_f32_e32 v8, v74, v14
	v_fmac_f32_e32 v0, v62, v7
	v_fmac_f32_e32 v8, v78, v15
	v_mov_b32_e32 v1, v0
	v_mov_b32_e32 v2, v8
	s_nop 0
	v_permlane32_swap_b32_e32 v0, v1
	v_permlane32_swap_b32_e32 v8, v2
	v_add_f32_e32 v0, v0, v1
	v_add_f32_e32 v1, v8, v2
	v_cndmask_b32_e64 v0, v1, v0, s[8:9]
	ds_write_b32 v80, v0
	v_max_i32_e32 v206, 0, v206
	v_max_i32_e32 v214, 0, v214
	v_max_i32_e32 v207, 0, v207
	v_max_i32_e32 v215, 0, v215
	v_fma_f32 v206, v40, v206, 0
	v_fma_f32 v214, v64, v214, 0
	v_max_i32_e32 v208, 0, v208
	v_max_i32_e32 v216, 0, v216
	v_fmac_f32_e32 v206, v52, v207
	v_fmac_f32_e32 v214, v68, v215
	v_max_i32_e32 v209, 0, v209
	v_max_i32_e32 v217, 0, v217
	v_fmac_f32_e32 v206, v56, v208
	v_fmac_f32_e32 v214, v72, v216
	v_max_i32_e32 v210, 0, v210
	v_max_i32_e32 v218, 0, v218
	v_fmac_f32_e32 v206, v60, v209
	v_fmac_f32_e32 v214, v76, v217
	v_max_i32_e32 v211, 0, v211
	v_max_i32_e32 v219, 0, v219
	v_fmac_f32_e32 v206, v50, v210
	v_fmac_f32_e32 v214, v66, v218
	v_max_i32_e32 v212, 0, v212
	v_max_i32_e32 v220, 0, v220
	v_fmac_f32_e32 v206, v54, v211
	v_fmac_f32_e32 v214, v70, v219
	v_max_i32_e32 v213, 0, v213
	v_max_i32_e32 v221, 0, v221
	v_fmac_f32_e32 v206, v58, v212
	v_fmac_f32_e32 v214, v74, v220
	v_fmac_f32_e32 v206, v62, v213
	v_fmac_f32_e32 v214, v78, v221
	v_mov_b32_e32 v207, v206
	v_mov_b32_e32 v208, v214
	s_nop 0
	v_permlane32_swap_b32_e32 v206, v207
	v_permlane32_swap_b32_e32 v214, v208
	v_add_f32_e32 v206, v206, v207
	v_add_f32_e32 v207, v214, v208
	v_cndmask_b32_e64 v206, v207, v206, s[8:9]
	ds_write_b32 v80, v206 offset:128
	v_add_u32_e32 v80, 0x100, v80
	s_waitcnt lgkmcnt(0)
	s_barrier
	s_cbranch_scc1 .LBB0_600
